# NA: Q fragments retired before the unit barrier; QK head waits only on LDS so the next unit K/V prefetch stays in flight
# speedup vs baseline: 1.0020x; 1.0020x over previous
; #define LAS __attribute__((address_space(3)))
; DI f32x4 mfma32(bf16x8 a, bf16x8 b, f32x4 c) { return __builtin_amdgcn_mfma_f32_16x16x32_bf16(a, b, c, 0, 0, 0); }
; DI void phase_na(const Ctx& c, LAS unsigned char* lds, int g, int l, const bf16* PROJ, bf16* MIX, int bid, int nb, int tid) {
;     ...
;         for (int t = 0; t < 16; ++t) { const int rr = t >> 1, hf = t & 1, kr = r0 + rr;
;             const int krw_ = (kr - rbase) * 64 + kb0 + 16 * hf + li; const LAS unsigned char* kb_ = Kimg + krw_ * 128;
;             const bf16x8 ka_ = *(const LAS bf16x8*)(kb_ + ((gq ^ (krw_ & 7)) << 4)), kb2_ = *(const LAS bf16x8*)(kb_ + (((4 + gq) ^ (krw_ & 7)) << 4));
;             f32x4 sv = {0.f, 0.f, 0.f, 0.f}; sv = mfma32(ka_, qf0, sv); sv = mfma32(kb2_, qf1, sv);
;             const int dr = kr - r + 7;
; #pragma unroll
;             for (int j = 0; j < 4; ++j) sc[t][j] = sv[j] + rpbs[dr * 32 + dcx[hf * 4 + j]]; }
.LBB0_211:
	s_add_i32 s18, s18, -4
	s_min_i32 s0, s18, s62
	v_add_u32_e32 v91, -4, v93
	v_min_i32_e32 v91, s62, v91
	s_cmp_gt_u32 s1, 1
	v_cmp_lt_i32_e32 vcc, 3, v93
	s_cselect_b32 s0, s0, 0
	s_nop 0
	v_cndmask_b32_e32 v157, 0, v91, vcc
	v_subrev_u32_e32 v91, s0, v157
	v_lshl_add_u32 v142, v91, 13, v111
	v_add_u32_e32 v146, v142, v108
	ds_read_b128 v[138:141], v146
	v_add_u32_e32 v147, v142, v109
	ds_read_b128 v[142:145], v147
	v_add_u32_e32 v154, 1, v157
	s_waitcnt lgkmcnt(1)
	v_mfma_f32_16x16x32_bf16 v[138:141], v[138:141], v[78:81], 0
	v_lshlrev_b32_e32 v91, 6, v91
	s_waitcnt lgkmcnt(0)
	v_mfma_f32_16x16x32_bf16 v[142:145], v[142:145], v[82:85], v[138:141]
	s_nop 4
	v_sub_u32_e32 v138, v157, v93
	v_lshl_add_u32 v150, v138, 7, s26
	v_add_u32_e32 v138, v150, v130
	ds_read_b32 v138, v138 offset:896
	s_waitcnt lgkmcnt(0)
	v_add_f32_e32 v141, v142, v138
	v_add_u32_e32 v138, v150, v131
	ds_read_b32 v138, v138 offset:896
	s_waitcnt lgkmcnt(0)
	v_add_f32_e32 v140, v143, v138
	v_add_u32_e32 v138, v150, v132
	ds_read_b32 v138, v138 offset:896
	s_waitcnt lgkmcnt(0)
	v_add_f32_e32 v139, v144, v138
	v_add_u32_e32 v138, v150, v133
	ds_read_b32 v138, v138 offset:896
	s_waitcnt lgkmcnt(0)
	v_add_f32_e32 v138, v145, v138
	ds_read_b128 v[142:145], v146 offset:2048
	ds_read_b128 v[146:149], v147 offset:2048
	s_waitcnt lgkmcnt(1)
	v_mfma_f32_16x16x32_bf16 v[142:145], v[142:145], v[78:81], 0
	s_waitcnt lgkmcnt(0)
	v_mfma_f32_16x16x32_bf16 v[142:145], v[146:149], v[82:85], v[142:145]
	v_add_u32_e32 v146, v150, v134
	ds_read_b32 v146, v146 offset:896
	s_waitcnt lgkmcnt(0)
	s_nop 4
	v_add_f32_e32 v142, v142, v146
	v_add_u32_e32 v146, v150, v135
	ds_read_b32 v146, v146 offset:896
	s_waitcnt lgkmcnt(0)
	v_add_f32_e32 v143, v143, v146
	v_add_u32_e32 v146, v150, v136
	ds_read_b32 v146, v146 offset:896
	s_waitcnt lgkmcnt(0)
	v_add_f32_e32 v144, v144, v146
	v_add_u32_e32 v146, v150, v137
	ds_read_b32 v146, v146 offset:896
	s_waitcnt lgkmcnt(0)
	v_add_f32_e32 v145, v145, v146
	v_subrev_u32_e32 v146, s0, v154
	v_lshl_add_u32 v150, v146, 13, v111
	v_add_u32_e32 v155, v150, v108
	ds_read_b128 v[146:149], v155
	v_add_u32_e32 v156, v150, v109
	ds_read_b128 v[150:153], v156
	s_waitcnt lgkmcnt(1)
	v_mfma_f32_16x16x32_bf16 v[146:149], v[146:149], v[78:81], 0
	s_waitcnt lgkmcnt(0)
	v_mfma_f32_16x16x32_bf16 v[150:153], v[150:153], v[82:85], v[146:149]
	s_nop 5
	v_sub_u32_e32 v146, v154, v93
	v_lshl_add_u32 v154, v146, 7, s26
	v_add_u32_e32 v146, v154, v130
	ds_read_b32 v146, v146 offset:896
	s_waitcnt lgkmcnt(0)
	v_add_f32_e32 v149, v150, v146
	v_add_u32_e32 v146, v154, v131
	ds_read_b32 v146, v146 offset:896
	s_waitcnt lgkmcnt(0)
	v_add_f32_e32 v148, v151, v146
	v_add_u32_e32 v146, v154, v132
	ds_read_b32 v146, v146 offset:896
	s_waitcnt lgkmcnt(0)
	v_add_f32_e32 v147, v152, v146
	v_add_u32_e32 v146, v154, v133
	ds_read_b32 v146, v146 offset:896
	s_waitcnt lgkmcnt(0)
	v_add_f32_e32 v146, v153, v146
	ds_read_b128 v[150:153], v155 offset:2048
	ds_read_b128 v[164:167], v156 offset:2048
	s_waitcnt lgkmcnt(1)
	v_mfma_f32_16x16x32_bf16 v[150:153], v[150:153], v[78:81], 0
	v_add_u32_e32 v155, v154, v134
	ds_read_b32 v155, v155 offset:896
	s_waitcnt lgkmcnt(1)
	v_mfma_f32_16x16x32_bf16 v[150:153], v[164:167], v[82:85], v[150:153]
	s_waitcnt lgkmcnt(0)
	s_nop 6
	v_add_f32_e32 v150, v150, v155
	v_add_u32_e32 v155, v154, v135
	ds_read_b32 v155, v155 offset:896
	s_waitcnt lgkmcnt(0)
	v_add_f32_e32 v151, v151, v155
	v_add_u32_e32 v155, v154, v136
	v_add_u32_e32 v154, v154, v137
	ds_read_b32 v155, v155 offset:896
	ds_read_b32 v154, v154 offset:896
	s_waitcnt lgkmcnt(1)
	v_add_f32_e32 v152, v152, v155
	s_waitcnt lgkmcnt(0)
	v_add_f32_e32 v153, v153, v154
	v_add_u32_e32 v154, 2, v157
	v_subrev_u32_e32 v155, s0, v154
	v_lshl_add_u32 v155, v155, 13, v111
	v_add_u32_e32 v160, v155, v108
	ds_read_b128 v[164:167], v160
	v_add_u32_e32 v161, v155, v109
	ds_read_b128 v[168:171], v161
	v_sub_u32_e32 v154, v154, v93
	v_lshl_add_u32 v172, v154, 7, s26
	v_add_u32_e32 v154, v172, v130
	ds_read_b32 v154, v154 offset:896
	s_waitcnt lgkmcnt(2)
	v_mfma_f32_16x16x32_bf16 v[164:167], v[164:167], v[78:81], 0
	s_waitcnt lgkmcnt(1)
	v_mfma_f32_16x16x32_bf16 v[164:167], v[168:171], v[82:85], v[164:167]
	s_waitcnt lgkmcnt(0)
	s_nop 6
	v_add_f32_e32 v159, v164, v154
	v_add_u32_e32 v154, v172, v131
	ds_read_b32 v154, v154 offset:896
	s_waitcnt lgkmcnt(0)
	v_add_f32_e32 v156, v165, v154
	v_add_u32_e32 v154, v172, v132
	ds_read_b32 v154, v154 offset:896
	s_waitcnt lgkmcnt(0)
	v_add_f32_e32 v155, v166, v154
	v_add_u32_e32 v154, v172, v133
	ds_read_b32 v154, v154 offset:896
	s_waitcnt lgkmcnt(0)
	v_add_f32_e32 v154, v167, v154
	ds_read_b128 v[164:167], v160 offset:2048
	ds_read_b128 v[168:171], v161 offset:2048
	s_waitcnt lgkmcnt(1)
	v_mfma_f32_16x16x32_bf16 v[164:167], v[164:167], v[78:81], 0
	v_add_u32_e32 v160, v172, v134
	ds_read_b32 v160, v160 offset:896
	s_waitcnt lgkmcnt(1)
	v_mfma_f32_16x16x32_bf16 v[164:167], v[168:171], v[82:85], v[164:167]
	s_waitcnt lgkmcnt(0)
	s_nop 6
	v_add_f32_e32 v164, v164, v160
	v_add_u32_e32 v160, v172, v135
	ds_read_b32 v160, v160 offset:896
	s_waitcnt lgkmcnt(0)
	v_add_f32_e32 v165, v165, v160
	v_add_u32_e32 v160, v172, v136
	ds_read_b32 v160, v160 offset:896
	s_waitcnt lgkmcnt(0)
	v_add_f32_e32 v166, v166, v160
	v_add_u32_e32 v160, v172, v137
	ds_read_b32 v160, v160 offset:896
	s_waitcnt lgkmcnt(0)
	v_add_f32_e32 v167, v167, v160
	v_add_u32_e32 v160, 3, v157
	v_subrev_u32_e32 v161, s0, v160
	v_lshl_add_u32 v161, v161, 13, v111
	v_add_u32_e32 v176, v161, v108
	ds_read_b128 v[168:171], v176
	v_add_u32_e32 v161, v161, v109
	ds_read_b128 v[172:175], v161
	s_waitcnt lgkmcnt(1)
; #define LAS __attribute__((address_space(3)))
; DI f32x4 mfma32(bf16x8 a, bf16x8 b, f32x4 c) { return __builtin_amdgcn_mfma_f32_16x16x32_bf16(a, b, c, 0, 0, 0); }
; DI void phase_na(const Ctx& c, LAS unsigned char* lds, int g, int l, const bf16* PROJ, bf16* MIX, int bid, int nb, int tid) {
;     ...
;         for (int t = 0; t < 16; ++t) { const int rr = t >> 1, hf = t & 1, kr = r0 + rr;
;             const int krw_ = (kr - rbase) * 64 + kb0 + 16 * hf + li; const LAS unsigned char* kb_ = Kimg + krw_ * 128;
;             const bf16x8 ka_ = *(const LAS bf16x8*)(kb_ + ((gq ^ (krw_ & 7)) << 4)), kb2_ = *(const LAS bf16x8*)(kb_ + (((4 + gq) ^ (krw_ & 7)) << 4));
;             f32x4 sv = {0.f, 0.f, 0.f, 0.f}; sv = mfma32(ka_, qf0, sv); sv = mfma32(kb2_, qf1, sv);
;             const int dr = kr - r + 7;
; #pragma unroll
;             for (int j = 0; j < 4; ++j) sc[t][j] = sv[j] + rpbs[dr * 32 + dcx[hf * 4 + j]]; }
	v_mfma_f32_16x16x32_bf16 v[168:171], v[168:171], v[78:81], 0
	v_sub_u32_e32 v160, v160, v93
	v_lshl_add_u32 v160, v160, 7, s26
	s_waitcnt lgkmcnt(0)
	v_mfma_f32_16x16x32_bf16 v[172:175], v[172:175], v[82:85], v[168:171]
	s_nop 3
	v_add_u32_e32 v168, v160, v130
	ds_read_b32 v168, v168 offset:896
	s_waitcnt lgkmcnt(0)
	s_nop 0
	v_add_f32_e32 v171, v172, v168
	v_add_u32_e32 v168, v160, v131
	ds_read_b32 v168, v168 offset:896
	s_waitcnt lgkmcnt(0)
	v_add_f32_e32 v170, v173, v168
	v_add_u32_e32 v168, v160, v132
	ds_read_b32 v168, v168 offset:896
	s_waitcnt lgkmcnt(0)
	v_add_f32_e32 v169, v174, v168
	v_add_u32_e32 v168, v160, v133
	ds_read_b32 v168, v168 offset:896
	s_waitcnt lgkmcnt(0)
	v_add_f32_e32 v168, v175, v168
	ds_read_b128 v[172:175], v176 offset:2048
	ds_read_b128 v[176:179], v161 offset:2048
	s_waitcnt lgkmcnt(1)
	v_mfma_f32_16x16x32_bf16 v[172:175], v[172:175], v[78:81], 0
	v_add_u32_e32 v161, v160, v134
	ds_read_b32 v161, v161 offset:896
	s_waitcnt lgkmcnt(1)
	v_mfma_f32_16x16x32_bf16 v[172:175], v[176:179], v[82:85], v[172:175]
	s_waitcnt lgkmcnt(0)
	s_nop 6
	v_add_f32_e32 v172, v172, v161
	v_add_u32_e32 v161, v160, v135
	ds_read_b32 v161, v161 offset:896
	s_waitcnt lgkmcnt(0)
	v_add_f32_e32 v173, v173, v161
	v_add_u32_e32 v161, v160, v136
	v_add_u32_e32 v160, v160, v137
	ds_read_b32 v161, v161 offset:896
	ds_read_b32 v160, v160 offset:896
	s_waitcnt lgkmcnt(1)
	v_add_f32_e32 v174, v174, v161
	s_waitcnt lgkmcnt(0)
	v_add_f32_e32 v176, v175, v160
	v_add_u32_e32 v160, 4, v157
	v_subrev_u32_e32 v161, s0, v160
	v_lshl_add_u32 v161, v161, 13, v111
	v_add_u32_e32 v175, v161, v108
	ds_read_b128 v[178:181], v175
	v_add_u32_e32 v161, v161, v109
	ds_read_b128 v[182:185], v161
	s_waitcnt lgkmcnt(1)
	v_mfma_f32_16x16x32_bf16 v[178:181], v[178:181], v[78:81], 0
	v_sub_u32_e32 v160, v160, v93
	v_lshl_add_u32 v160, v160, 7, s26
	v_add_u32_e32 v177, v160, v130
	ds_read_b32 v177, v177 offset:896
	s_waitcnt lgkmcnt(1)
	v_mfma_f32_16x16x32_bf16 v[182:185], v[182:185], v[82:85], v[178:181]
	s_waitcnt lgkmcnt(0)
	s_nop 6
	v_add_f32_e32 v182, v182, v177
	v_add_u32_e32 v177, v160, v131
	ds_read_b32 v177, v177 offset:896
	s_waitcnt lgkmcnt(0)
	v_add_f32_e32 v181, v183, v177
	v_add_u32_e32 v177, v160, v132
	ds_read_b32 v177, v177 offset:896
	s_waitcnt lgkmcnt(0)
	v_add_f32_e32 v180, v184, v177
	v_add_u32_e32 v177, v160, v133
	ds_read_b32 v177, v177 offset:896
	s_waitcnt lgkmcnt(0)
	v_add_f32_e32 v179, v185, v177
	ds_read_b128 v[184:187], v175 offset:2048
	ds_read_b128 v[188:191], v161 offset:2048
	s_waitcnt lgkmcnt(1)
	v_mfma_f32_16x16x32_bf16 v[184:187], v[184:187], v[78:81], 0
	v_add_u32_e32 v161, v160, v134
	ds_read_b32 v161, v161 offset:896
	s_waitcnt lgkmcnt(1)
	v_mfma_f32_16x16x32_bf16 v[184:187], v[188:191], v[82:85], v[184:187]
	s_waitcnt lgkmcnt(0)
	s_nop 6
	v_add_f32_e32 v191, v184, v161
	v_add_u32_e32 v161, v160, v135
	ds_read_b32 v161, v161 offset:896
	s_waitcnt lgkmcnt(0)
	v_add_f32_e32 v192, v185, v161
	v_add_u32_e32 v161, v160, v136
	v_add_u32_e32 v160, v160, v137
	ds_read_b32 v161, v161 offset:896
	ds_read_b32 v160, v160 offset:896
	s_waitcnt lgkmcnt(1)
	v_add_f32_e32 v193, v186, v161
	s_waitcnt lgkmcnt(0)
	v_add_f32_e32 v194, v187, v160
	v_add_u32_e32 v160, 5, v157
	v_subrev_u32_e32 v161, s0, v160
	v_lshl_add_u32 v161, v161, 13, v111
	v_add_u32_e32 v175, v161, v108
	ds_read_b128 v[184:187], v175
	v_add_u32_e32 v161, v161, v109
	ds_read_b128 v[196:199], v161
	s_waitcnt lgkmcnt(1)
	v_mfma_f32_16x16x32_bf16 v[184:187], v[184:187], v[78:81], 0
	v_sub_u32_e32 v160, v160, v93
	v_lshl_add_u32 v160, v160, 7, s26
	v_add_u32_e32 v177, v160, v130
	ds_read_b32 v177, v177 offset:896
	s_waitcnt lgkmcnt(1)
	v_mfma_f32_16x16x32_bf16 v[184:187], v[196:199], v[82:85], v[184:187]
	s_waitcnt lgkmcnt(0)
	s_nop 6
	v_add_f32_e32 v204, v184, v177
	v_add_u32_e32 v177, v160, v131
	ds_read_b32 v177, v177 offset:896
	s_waitcnt lgkmcnt(0)
	v_add_f32_e32 v203, v185, v177
	v_add_u32_e32 v177, v160, v132
	ds_read_b32 v177, v177 offset:896
	s_waitcnt lgkmcnt(0)
	v_add_f32_e32 v201, v186, v177
	v_add_u32_e32 v177, v160, v133
	ds_read_b32 v177, v177 offset:896
	s_waitcnt lgkmcnt(0)
	v_add_f32_e32 v200, v187, v177
	ds_read_b128 v[184:187], v175 offset:2048
	ds_read_b128 v[196:199], v161 offset:2048
	s_waitcnt lgkmcnt(1)
	v_mfma_f32_16x16x32_bf16 v[184:187], v[184:187], v[78:81], 0
	v_add_u32_e32 v161, v160, v134
	ds_read_b32 v161, v161 offset:896
	s_waitcnt lgkmcnt(1)
	v_mfma_f32_16x16x32_bf16 v[184:187], v[196:199], v[82:85], v[184:187]
	s_waitcnt lgkmcnt(0)
	s_nop 6
	v_add_f32_e32 v213, v184, v161
	v_add_u32_e32 v161, v160, v135
	ds_read_b32 v161, v161 offset:896
	s_waitcnt lgkmcnt(0)
	v_add_f32_e32 v219, v185, v161
	v_add_u32_e32 v161, v160, v136
	v_add_u32_e32 v160, v160, v137
	ds_read_b32 v161, v161 offset:896
	ds_read_b32 v160, v160 offset:896
	s_waitcnt lgkmcnt(1)
	v_add_f32_e32 v220, v186, v161
	s_waitcnt lgkmcnt(0)
	v_add_f32_e32 v222, v187, v160
	v_add_u32_e32 v160, 6, v157
	v_subrev_u32_e32 v161, s0, v160
	v_lshl_add_u32 v161, v161, 13, v111
	v_add_u32_e32 v175, v161, v108
	ds_read_b128 v[184:187], v175
	v_add_u32_e32 v161, v161, v109
	ds_read_b128 v[196:199], v161
	s_waitcnt lgkmcnt(1)
	v_mfma_f32_16x16x32_bf16 v[184:187], v[184:187], v[78:81], 0
	v_sub_u32_e32 v160, v160, v93
	v_lshl_add_u32 v160, v160, 7, s26
	v_add_u32_e32 v177, v160, v130
	ds_read_b32 v177, v177 offset:896
	s_waitcnt lgkmcnt(1)
	v_mfma_f32_16x16x32_bf16 v[184:187], v[196:199], v[82:85], v[184:187]
	v_add_u32_e32 v157, 7, v157
	v_sub_u32_e32 v93, v157, v93
	s_waitcnt lgkmcnt(0)
	s_nop 4
	v_add_f32_e32 v226, v184, v177
	v_add_u32_e32 v177, v160, v131
	ds_read_b32 v177, v177 offset:896
	s_waitcnt lgkmcnt(0)
; #define LAS __attribute__((address_space(3)))
; DI f32x4 mfma32(bf16x8 a, bf16x8 b, f32x4 c) { return __builtin_amdgcn_mfma_f32_16x16x32_bf16(a, b, c, 0, 0, 0); }
; DI void phase_na(const Ctx& c, LAS unsigned char* lds, int g, int l, const bf16* PROJ, bf16* MIX, int bid, int nb, int tid) {
;     ...
;         for (int t = 0; t < 16; ++t) { const int rr = t >> 1, hf = t & 1, kr = r0 + rr;
;             const int krw_ = (kr - rbase) * 64 + kb0 + 16 * hf + li; const LAS unsigned char* kb_ = Kimg + krw_ * 128;
;             const bf16x8 ka_ = *(const LAS bf16x8*)(kb_ + ((gq ^ (krw_ & 7)) << 4)), kb2_ = *(const LAS bf16x8*)(kb_ + (((4 + gq) ^ (krw_ & 7)) << 4));
;             f32x4 sv = {0.f, 0.f, 0.f, 0.f}; sv = mfma32(ka_, qf0, sv); sv = mfma32(kb2_, qf1, sv);
;             const int dr = kr - r + 7;
; #pragma unroll
;             for (int j = 0; j < 4; ++j) sc[t][j] = sv[j] + rpbs[dr * 32 + dcx[hf * 4 + j]]; }
;         float m = -3e38f;
; #pragma unroll
;         for (int t = 0; t < 16; ++t)
; #pragma unroll
;             for (int j = 0; j < 4; ++j) m = fmaxf(m, sc[t][j]);
;         m = fmaxf(m, __shfl_xor(m, 16)); m = fmaxf(m, __shfl_xor(m, 32));
;         float sum = 0.f;
; #pragma unroll
;         for (int t = 0; t < 16; ++t)
; #pragma unroll
;             for (int j = 0; j < 4; ++j) { const float p = __expf(sc[t][j] - m); sc[t][j] = p; sum += p; }
	v_add_f32_e32 v225, v185, v177
	v_add_u32_e32 v177, v160, v132
	ds_read_b32 v177, v177 offset:896
	s_waitcnt lgkmcnt(0)
	v_add_f32_e32 v224, v186, v177
	v_add_u32_e32 v177, v160, v133
	ds_read_b32 v177, v177 offset:896
	s_waitcnt lgkmcnt(0)
	v_add_f32_e32 v223, v187, v177
	ds_read_b128 v[184:187], v175 offset:2048
	ds_read_b128 v[196:199], v161 offset:2048
	s_waitcnt lgkmcnt(1)
	v_mfma_f32_16x16x32_bf16 v[184:187], v[184:187], v[78:81], 0
	v_add_u32_e32 v161, v160, v134
	ds_read_b32 v161, v161 offset:896
	s_waitcnt lgkmcnt(1)
	v_mfma_f32_16x16x32_bf16 v[184:187], v[196:199], v[82:85], v[184:187]
	s_waitcnt lgkmcnt(0)
	s_nop 6
	v_add_f32_e32 v227, v184, v161
	v_add_u32_e32 v161, v160, v135
	ds_read_b32 v161, v161 offset:896
	s_waitcnt lgkmcnt(0)
	v_add_f32_e32 v228, v185, v161
	v_add_u32_e32 v161, v160, v136
	v_add_u32_e32 v160, v160, v137
	ds_read_b32 v161, v161 offset:896
	ds_read_b32 v160, v160 offset:896
	s_waitcnt lgkmcnt(1)
	v_add_f32_e32 v229, v186, v161
	s_waitcnt lgkmcnt(0)
	v_add_f32_e32 v230, v187, v160
	v_subrev_u32_e32 v160, s0, v157
	v_lshl_add_u32 v160, v160, 13, v111
	v_add_u32_e32 v161, v160, v108
	ds_read_b128 v[184:187], v161
	v_add_u32_e32 v160, v160, v109
	ds_read_b128 v[196:199], v160
	s_waitcnt lgkmcnt(1)
	v_mfma_f32_16x16x32_bf16 v[184:187], v[184:187], v[78:81], 0
	v_lshl_add_u32 v157, v93, 7, s26
	v_add_u32_e32 v93, v157, v130
	ds_read_b32 v93, v93 offset:896
	s_waitcnt lgkmcnt(1)
	v_mfma_f32_16x16x32_bf16 v[184:187], v[196:199], v[82:85], v[184:187]
	v_add_u32_e32 v175, v157, v133
	ds_read_b32 v175, v175 offset:896
	s_mov_b32 s0, 0xff61b1e6
	s_waitcnt lgkmcnt(1)
	s_nop 3
	v_add_f32_e32 v233, v184, v93
	v_add_u32_e32 v93, v157, v131
	ds_read_b32 v93, v93 offset:896
	s_waitcnt lgkmcnt(1)
	v_add_f32_e32 v231, v187, v175
	s_waitcnt lgkmcnt(0)
	v_add_f32_e32 v232, v185, v93
	v_add_u32_e32 v93, v157, v132
	ds_read_b32 v93, v93 offset:896
	s_waitcnt lgkmcnt(0)
	v_add_f32_e32 v93, v186, v93
	ds_read_b128 v[184:187], v161 offset:2048
	ds_read_b128 v[196:199], v160 offset:2048
	s_waitcnt lgkmcnt(1)
	v_mfma_f32_16x16x32_bf16 v[78:81], v[184:187], v[78:81], 0
	s_waitcnt lgkmcnt(0)
	v_mfma_f32_16x16x32_bf16 v[78:81], v[196:199], v[82:85], v[78:81]
	v_add_u32_e32 v82, v157, v134
	ds_read_b32 v82, v82 offset:896
	s_waitcnt lgkmcnt(0)
	s_nop 4
	v_add_f32_e32 v78, v78, v82
	v_add_u32_e32 v82, v157, v135
	ds_read_b32 v82, v82 offset:896
	s_waitcnt lgkmcnt(0)
	v_add_f32_e32 v79, v79, v82
	v_add_u32_e32 v82, v157, v136
	ds_read_b32 v82, v82 offset:896
	s_waitcnt lgkmcnt(0)
	v_add_f32_e32 v82, v80, v82
	v_add_u32_e32 v80, v157, v137
	ds_read_b32 v80, v80 offset:896
	s_waitcnt lgkmcnt(0)
	v_add_f32_e32 v83, v81, v80
	v_max3_f32 v80, v141, s0, v140
	v_max3_f32 v80, v80, v139, v138
	v_max3_f32 v80, v80, v142, v143
	v_max3_f32 v80, v80, v144, v145
	v_max3_f32 v80, v80, v149, v148
	v_max3_f32 v80, v80, v147, v146
	v_max3_f32 v80, v80, v150, v151
	v_max3_f32 v80, v80, v152, v153
	v_max3_f32 v80, v80, v159, v156
	v_max3_f32 v80, v80, v155, v154
	v_max3_f32 v80, v80, v164, v165
	v_max3_f32 v80, v80, v166, v167
	v_max3_f32 v80, v80, v171, v170
	v_max3_f32 v80, v80, v169, v168
	v_max3_f32 v80, v80, v172, v173
	v_max3_f32 v80, v80, v174, v176
	v_max3_f32 v80, v80, v182, v181
	v_max3_f32 v80, v80, v180, v179
	v_max3_f32 v80, v80, v191, v192
	v_max3_f32 v80, v80, v193, v194
	v_max3_f32 v80, v80, v204, v203
	v_max3_f32 v80, v80, v201, v200
	v_max3_f32 v80, v80, v213, v219
	v_max3_f32 v80, v80, v220, v222
	v_max3_f32 v80, v80, v226, v225
	v_max3_f32 v80, v80, v224, v223
	v_max3_f32 v80, v80, v227, v228
	v_max3_f32 v80, v80, v229, v230
	v_max3_f32 v80, v80, v233, v232
	v_max3_f32 v80, v80, v93, v231
	v_max3_f32 v80, v80, v78, v79
	v_max3_f32 v80, v80, v82, v83
	ds_bpermute_b32 v81, v105, v80
	s_waitcnt lgkmcnt(0)
	v_max_f32_e32 v81, v81, v81
	v_max_f32_e32 v80, v80, v81
	ds_bpermute_b32 v81, v106, v80
	s_waitcnt lgkmcnt(0)
	v_max_f32_e32 v81, v81, v81
	v_max_f32_e32 v160, v80, v81
	v_sub_f32_e32 v81, v140, v160
	v_mul_f32_e32 v81, 0x3fb8aa3b, v81
	v_exp_f32_e32 v212, v81
	v_sub_f32_e32 v81, v139, v160
	v_mul_f32_e32 v81, 0x3fb8aa3b, v81
	v_exp_f32_e32 v218, v81
	v_sub_f32_e32 v81, v138, v160
	v_mul_f32_e32 v81, 0x3fb8aa3b, v81
	v_exp_f32_e32 v221, v81
	v_sub_f32_e32 v81, v142, v160
	v_mul_f32_e32 v81, 0x3fb8aa3b, v81
	v_exp_f32_e32 v207, v81
	v_sub_f32_e32 v81, v143, v160
	v_mul_f32_e32 v81, 0x3fb8aa3b, v81
	v_exp_f32_e32 v208, v81
	v_sub_f32_e32 v81, v144, v160
	v_mul_f32_e32 v81, 0x3fb8aa3b, v81
	v_exp_f32_e32 v209, v81
	v_sub_f32_e32 v81, v145, v160
	v_mul_f32_e32 v81, 0x3fb8aa3b, v81
	v_exp_f32_e32 v211, v81
	v_sub_f32_e32 v81, v149, v160
	v_mul_f32_e32 v81, 0x3fb8aa3b, v81
	v_exp_f32_e32 v198, v81
	v_sub_f32_e32 v81, v148, v160
	v_mul_f32_e32 v81, 0x3fb8aa3b, v81
	v_exp_f32_e32 v199, v81
	v_sub_f32_e32 v81, v147, v160
	v_mul_f32_e32 v81, 0x3fb8aa3b, v81
	v_exp_f32_e32 v205, v81
	v_sub_f32_e32 v81, v146, v160
	v_mul_f32_e32 v81, 0x3fb8aa3b, v81
	v_exp_f32_e32 v206, v81
	v_sub_f32_e32 v81, v150, v160
	v_mul_f32_e32 v81, 0x3fb8aa3b, v81
	v_exp_f32_e32 v195, v81
	v_sub_f32_e32 v81, v151, v160
	v_mul_f32_e32 v81, 0x3fb8aa3b, v81
	v_exp_f32_e32 v196, v81
	v_sub_f32_e32 v81, v152, v160
	v_mul_f32_e32 v81, 0x3fb8aa3b, v81
	v_exp_f32_e32 v197, v81
	v_sub_f32_e32 v81, v153, v160
	v_mul_f32_e32 v81, 0x3fb8aa3b, v81
	v_exp_f32_e32 v202, v81
	v_sub_f32_e32 v81, v159, v160
	v_mul_f32_e32 v81, 0x3fb8aa3b, v81
	v_exp_f32_e32 v186, v81
	v_sub_f32_e32 v81, v156, v160
	v_mul_f32_e32 v81, 0x3fb8aa3b, v81
	v_exp_f32_e32 v187, v81
	v_sub_f32_e32 v81, v155, v160
	v_mul_f32_e32 v81, 0x3fb8aa3b, v81
	v_exp_f32_e32 v189, v81
	v_sub_f32_e32 v81, v154, v160
; DI f32x4 mfma16(s16x4 a, s16x4 b, f32x4 c) { return __builtin_amdgcn_mfma_f32_16x16x16bf16_1k(a, b, c, 0, 0, 0); }
; DI s16x4 pack4(f32x4 v) { uint2 w; w.x = pk(v[0], v[1]); w.y = pk(v[2], v[3]); return __builtin_bit_cast(s16x4, w); }
; DI void phase_na(const Ctx& c, LAS unsigned char* lds, int g, int l, const bf16* PROJ, bf16* MIX, int bid, int nb, int tid) {
;     ...
;         float sum = 0.f;
; #pragma unroll
;         for (int t = 0; t < 16; ++t)
; #pragma unroll
;             for (int j = 0; j < 4; ++j) { const float p = __expf(sc[t][j] - m); sc[t][j] = p; sum += p; }
;         sum += __shfl_xor(sum, 16); sum += __shfl_xor(sum, 32);
;         f32x4 o[4];
; #pragma unroll
;         for (int dt = 0; dt < 4; ++dt) o[dt] = (f32x4){0.f, 0.f, 0.f, 0.f};
; #pragma unroll
;         for (int t = 0; t < 16; ++t) { const int rr = t >> 1, hf = t & 1, krow = (r0 + rr - rbase) * 64 + kb0 + 16 * hf; const s16x4 pb = pack4(sc[t]);
; #pragma unroll
;             for (int dt = 0; dt < 4; ++dt) o[dt] = mfma16(ld_tr4(Vimg, 72, krow, dt * 16, lane), pb, o[dt]); }
	v_mul_f32_e32 v81, 0x3fb8aa3b, v81
	v_exp_f32_e32 v190, v81
	v_sub_f32_e32 v81, v164, v160
	v_mul_f32_e32 v81, 0x3fb8aa3b, v81
	v_exp_f32_e32 v183, v81
	v_sub_f32_e32 v81, v165, v160
	v_mul_f32_e32 v81, 0x3fb8aa3b, v81
	v_exp_f32_e32 v184, v81
	v_sub_f32_e32 v81, v166, v160
	v_mul_f32_e32 v81, 0x3fb8aa3b, v81
	v_exp_f32_e32 v185, v81
	v_sub_f32_e32 v81, v167, v160
	v_mul_f32_e32 v81, 0x3fb8aa3b, v81
	v_exp_f32_e32 v188, v81
	v_sub_f32_e32 v81, v171, v160
	v_mul_f32_e32 v81, 0x3fb8aa3b, v81
	v_exp_f32_e32 v171, v81
	v_sub_f32_e32 v81, v170, v160
	v_mul_f32_e32 v81, 0x3fb8aa3b, v81
	v_exp_f32_e32 v175, v81
	v_sub_f32_e32 v81, v169, v160
	v_mul_f32_e32 v81, 0x3fb8aa3b, v81
	v_exp_f32_e32 v177, v81
	v_sub_f32_e32 v81, v168, v160
	v_mul_f32_e32 v81, 0x3fb8aa3b, v81
	v_exp_f32_e32 v178, v81
	v_sub_f32_e32 v81, v172, v160
	v_mul_f32_e32 v81, 0x3fb8aa3b, v81
	v_exp_f32_e32 v168, v81
	v_sub_f32_e32 v81, v173, v160
	v_sub_f32_e32 v80, v141, v160
	v_mul_f32_e32 v81, 0x3fb8aa3b, v81
	v_mul_f32_e32 v80, 0x3fb8aa3b, v80
	v_exp_f32_e32 v169, v81
	v_sub_f32_e32 v81, v174, v160
	v_exp_f32_e32 v210, v80
	v_mul_f32_e32 v81, 0x3fb8aa3b, v81
	v_exp_f32_e32 v170, v81
	v_sub_f32_e32 v81, v176, v160
	v_mul_f32_e32 v81, 0x3fb8aa3b, v81
	v_exp_f32_e32 v172, v81
	v_sub_f32_e32 v81, v182, v160
	v_add_f32_e32 v80, 0, v210
	v_mul_f32_e32 v81, 0x3fb8aa3b, v81
	v_add_f32_e32 v80, v212, v80
	v_exp_f32_e32 v164, v81
	v_sub_f32_e32 v81, v181, v160
	v_add_f32_e32 v80, v218, v80
	v_mul_f32_e32 v81, 0x3fb8aa3b, v81
	v_add_f32_e32 v80, v221, v80
	v_exp_f32_e32 v165, v81
	v_sub_f32_e32 v81, v180, v160
	v_add_f32_e32 v80, v207, v80
	v_mul_f32_e32 v81, 0x3fb8aa3b, v81
	v_add_f32_e32 v80, v208, v80
	v_exp_f32_e32 v166, v81
	v_sub_f32_e32 v81, v179, v160
	v_add_f32_e32 v80, v209, v80
	v_mul_f32_e32 v81, 0x3fb8aa3b, v81
	v_add_f32_e32 v80, v211, v80
	v_exp_f32_e32 v167, v81
	v_sub_f32_e32 v81, v191, v160
	v_add_f32_e32 v80, v198, v80
	v_mul_f32_e32 v81, 0x3fb8aa3b, v81
	v_add_f32_e32 v80, v199, v80
	v_exp_f32_e32 v155, v81
	v_sub_f32_e32 v81, v192, v160
	v_add_f32_e32 v80, v205, v80
	v_mul_f32_e32 v81, 0x3fb8aa3b, v81
	v_add_f32_e32 v80, v206, v80
	v_exp_f32_e32 v156, v81
	v_sub_f32_e32 v81, v193, v160
	v_add_f32_e32 v80, v195, v80
	v_mul_f32_e32 v81, 0x3fb8aa3b, v81
	v_add_f32_e32 v80, v196, v80
	v_exp_f32_e32 v157, v81
	v_sub_f32_e32 v81, v194, v160
	v_add_f32_e32 v80, v197, v80
	v_mul_f32_e32 v81, 0x3fb8aa3b, v81
	v_add_f32_e32 v80, v202, v80
	v_exp_f32_e32 v159, v81
	v_sub_f32_e32 v81, v204, v160
	v_add_f32_e32 v80, v186, v80
	v_mul_f32_e32 v81, 0x3fb8aa3b, v81
	v_add_f32_e32 v80, v187, v80
	v_exp_f32_e32 v151, v81
	v_sub_f32_e32 v81, v203, v160
	v_add_f32_e32 v80, v189, v80
	v_mul_f32_e32 v81, 0x3fb8aa3b, v81
	v_add_f32_e32 v80, v190, v80
	v_exp_f32_e32 v152, v81
	v_sub_f32_e32 v81, v201, v160
	v_add_f32_e32 v80, v183, v80
	v_mul_f32_e32 v81, 0x3fb8aa3b, v81
	v_add_f32_e32 v80, v184, v80
	v_exp_f32_e32 v153, v81
	v_sub_f32_e32 v81, v200, v160
	v_add_f32_e32 v80, v185, v80
	v_mul_f32_e32 v81, 0x3fb8aa3b, v81
	v_add_f32_e32 v80, v188, v80
	v_exp_f32_e32 v154, v81
	v_sub_f32_e32 v81, v213, v160
	v_add_f32_e32 v80, v171, v80
	v_mul_f32_e32 v81, 0x3fb8aa3b, v81
	v_add_f32_e32 v80, v175, v80
	v_exp_f32_e32 v147, v81
	v_sub_f32_e32 v81, v219, v160
	v_add_f32_e32 v80, v177, v80
	v_mul_f32_e32 v81, 0x3fb8aa3b, v81
	v_add_f32_e32 v80, v178, v80
	v_exp_f32_e32 v148, v81
	v_sub_f32_e32 v81, v220, v160
	v_add_f32_e32 v80, v168, v80
	v_mul_f32_e32 v81, 0x3fb8aa3b, v81
	v_add_f32_e32 v80, v169, v80
	v_exp_f32_e32 v149, v81
	v_sub_f32_e32 v81, v222, v160
	v_add_f32_e32 v80, v170, v80
	v_mul_f32_e32 v81, 0x3fb8aa3b, v81
	v_add_f32_e32 v80, v172, v80
	v_exp_f32_e32 v150, v81
	v_sub_f32_e32 v81, v226, v160
	v_add_f32_e32 v80, v164, v80
	v_mul_f32_e32 v81, 0x3fb8aa3b, v81
	v_add_f32_e32 v80, v165, v80
	v_exp_f32_e32 v143, v81
	v_sub_f32_e32 v81, v225, v160
	v_add_f32_e32 v80, v166, v80
	v_mul_f32_e32 v81, 0x3fb8aa3b, v81
	v_add_f32_e32 v80, v167, v80
	v_exp_f32_e32 v144, v81
	v_sub_f32_e32 v81, v224, v160
	v_add_f32_e32 v80, v155, v80
	v_mul_f32_e32 v81, 0x3fb8aa3b, v81
	v_add_f32_e32 v80, v156, v80
	v_exp_f32_e32 v145, v81
	v_sub_f32_e32 v81, v223, v160
	v_add_f32_e32 v80, v157, v80
	v_mul_f32_e32 v81, 0x3fb8aa3b, v81
	v_add_f32_e32 v80, v159, v80
	v_exp_f32_e32 v146, v81
	v_sub_f32_e32 v81, v227, v160
	v_add_f32_e32 v80, v151, v80
	v_mul_f32_e32 v81, 0x3fb8aa3b, v81
	v_add_f32_e32 v80, v152, v80
	v_exp_f32_e32 v139, v81
	v_sub_f32_e32 v81, v228, v160
	v_add_f32_e32 v80, v153, v80
	v_mul_f32_e32 v81, 0x3fb8aa3b, v81
	v_add_f32_e32 v80, v154, v80
	v_exp_f32_e32 v140, v81
	v_sub_f32_e32 v81, v229, v160
	v_add_f32_e32 v80, v147, v80
	v_mul_f32_e32 v81, 0x3fb8aa3b, v81
	v_add_f32_e32 v80, v148, v80
	v_exp_f32_e32 v141, v81
	v_sub_f32_e32 v81, v230, v160
	v_add_f32_e32 v80, v149, v80
	v_mul_f32_e32 v81, 0x3fb8aa3b, v81
	v_add_f32_e32 v80, v150, v80
	v_exp_f32_e32 v142, v81
	v_sub_f32_e32 v81, v233, v160
	v_add_f32_e32 v80, v143, v80
	v_mul_f32_e32 v81, 0x3fb8aa3b, v81
	v_add_f32_e32 v80, v144, v80
	v_exp_f32_e32 v84, v81
	v_sub_f32_e32 v81, v232, v160
	v_add_f32_e32 v80, v145, v80
	v_mul_f32_e32 v81, 0x3fb8aa3b, v81
	v_add_f32_e32 v80, v146, v80
	v_exp_f32_e32 v85, v81
	v_sub_f32_e32 v81, v93, v160
	v_add_f32_e32 v80, v139, v80
	v_mul_f32_e32 v81, 0x3fb8aa3b, v81
	v_add_f32_e32 v80, v140, v80
	v_exp_f32_e32 v93, v81
	v_sub_f32_e32 v81, v231, v160
	v_add_f32_e32 v80, v141, v80
	v_mul_f32_e32 v81, 0x3fb8aa3b, v81
	v_add_f32_e32 v80, v142, v80
	v_exp_f32_e32 v138, v81
	v_add_f32_e32 v80, v84, v80
	v_add_f32_e32 v80, v85, v80
	v_sub_f32_e32 v78, v78, v160
	v_add_f32_e32 v80, v93, v80
	v_mul_f32_e32 v78, 0x3fb8aa3b, v78
	v_add_f32_e32 v81, v138, v80
	v_exp_f32_e32 v80, v78
	v_sub_f32_e32 v79, v79, v160
	v_mul_f32_e32 v79, 0x3fb8aa3b, v79
	v_cvt_pk_bf16_f32 v180, v210, v212
	v_add_f32_e32 v78, v80, v81
	v_exp_f32_e32 v81, v79
	v_sub_f32_e32 v79, v82, v160
	v_mul_f32_e32 v79, 0x3fb8aa3b, v79
	v_exp_f32_e32 v82, v79
	v_sub_f32_e32 v79, v83, v160
	v_add_u32_e32 v160, v91, v107
	v_mad_u64_u32 v[192:193], s[0:1], v160, s27, v[88:89]
	ds_read_b64_tr_b16 v[200:201], v192
	ds_read_b64_tr_b16 v[212:213], v192 offset:32
	v_cvt_pk_bf16_f32 v181, v218, v221
	v_add_u32_e32 v160, v91, v110
	v_cvt_pk_bf16_f32 v156, v155, v156
	s_waitcnt lgkmcnt(1)
; DI f32x4 mfma16(s16x4 a, s16x4 b, f32x4 c) { return __builtin_amdgcn_mfma_f32_16x16x16bf16_1k(a, b, c, 0, 0, 0); }
; DI s16x4 pack4(f32x4 v) { uint2 w; w.x = pk(v[0], v[1]); w.y = pk(v[2], v[3]); return __builtin_bit_cast(s16x4, w); }
; DI void phase_na(const Ctx& c, LAS unsigned char* lds, int g, int l, const bf16* PROJ, bf16* MIX, int bid, int nb, int tid) {
;     ...
;         sum += __shfl_xor(sum, 16); sum += __shfl_xor(sum, 32);
;         f32x4 o[4];
; #pragma unroll
;         for (int dt = 0; dt < 4; ++dt) o[dt] = (f32x4){0.f, 0.f, 0.f, 0.f};
; #pragma unroll
;         for (int t = 0; t < 16; ++t) { const int rr = t >> 1, hf = t & 1, krow = (r0 + rr - rbase) * 64 + kb0 + 16 * hf; const s16x4 pb = pack4(sc[t]);
; #pragma unroll
;             for (int dt = 0; dt < 4; ++dt) o[dt] = mfma16(ld_tr4(Vimg, 72, krow, dt * 16, lane), pb, o[dt]); }
;         const float inv = 1.0f / sum;
	v_mfma_f32_16x16x16_bf16 v[218:221], v[200:201], v[180:181], 0
	ds_read_b64_tr_b16 v[200:201], v192 offset:64
	ds_read_b64_tr_b16 v[192:193], v192 offset:96
	v_cvt_pk_bf16_f32 v157, v157, v159
	s_waitcnt lgkmcnt(0)
	v_mfma_f32_16x16x16_bf16 v[230:233], v[192:193], v[180:181], 0
	v_mad_u64_u32 v[192:193], s[0:1], v160, s27, v[88:89]
	v_add_u32_e32 v160, 64, v91
	v_mfma_f32_16x16x16_bf16 v[222:225], v[212:213], v[180:181], 0
	v_add_u32_e32 v161, v160, v107
	v_add_u32_e32 v160, v160, v110
	v_add_u32_e32 v159, 0x140, v91
	v_mfma_f32_16x16x16_bf16 v[226:229], v[200:201], v[180:181], 0
	ds_read_b64_tr_b16 v[200:201], v192
	ds_read_b64_tr_b16 v[212:213], v192 offset:32
	v_cvt_pk_bf16_f32 v180, v207, v208
	v_cvt_pk_bf16_f32 v181, v209, v211
	v_cvt_pk_bf16_f32 v84, v84, v85
	v_cvt_pk_bf16_f32 v85, v93, v138
	s_waitcnt lgkmcnt(1)
	v_mfma_f32_16x16x16_bf16 v[208:211], v[200:201], v[180:181], v[218:221]
	ds_read_b64_tr_b16 v[200:201], v192 offset:64
	ds_read_b64_tr_b16 v[192:193], v192 offset:96
	v_mul_f32_e32 v79, 0x3fb8aa3b, v79
	s_waitcnt lgkmcnt(2)
	v_mfma_f32_16x16x16_bf16 v[218:221], v[212:213], v[180:181], v[222:225]
	v_mad_u64_u32 v[212:213], s[0:1], v160, s27, v[88:89]
	v_add_u32_e32 v160, 0x80, v91
	s_waitcnt lgkmcnt(1)
	v_mfma_f32_16x16x16_bf16 v[222:225], v[200:201], v[180:181], v[226:229]
	v_add_f32_e32 v78, v81, v78
	v_exp_f32_e32 v83, v79
	v_add_f32_e32 v78, v82, v78
	s_waitcnt lgkmcnt(0)
	v_mfma_f32_16x16x16_bf16 v[226:229], v[192:193], v[180:181], v[230:233]
	v_mad_u64_u32 v[192:193], s[0:1], v161, s27, v[88:89]
	v_cvt_pk_bf16_f32 v180, v198, v199
	v_cvt_pk_bf16_f32 v181, v205, v206
	ds_read_b64_tr_b16 v[198:199], v192
	ds_read_b64_tr_b16 v[204:205], v192 offset:32
	s_waitcnt lgkmcnt(1)
	v_mfma_f32_16x16x16_bf16 v[198:201], v[198:199], v[180:181], v[208:211]
	s_nop 2
	ds_read_b64_tr_b16 v[208:209], v192 offset:64
	ds_read_b64_tr_b16 v[192:193], v192 offset:96
	v_add_u32_e32 v161, v160, v107
	s_waitcnt lgkmcnt(2)
	v_mfma_f32_16x16x16_bf16 v[204:207], v[204:205], v[180:181], v[218:221]
	v_add_u32_e32 v160, v160, v110
	v_add_f32_e32 v78, v83, v78
	ds_bpermute_b32 v79, v105, v78
	s_waitcnt lgkmcnt(2)
	v_mfma_f32_16x16x16_bf16 v[208:211], v[208:209], v[180:181], v[222:225]
	s_waitcnt lgkmcnt(0)
	v_add_f32_e32 v78, v78, v79
	ds_bpermute_b32 v79, v106, v78
	v_mfma_f32_16x16x16_bf16 v[218:221], v[192:193], v[180:181], v[226:229]
	v_cvt_pk_bf16_f32 v180, v195, v196
	v_cvt_pk_bf16_f32 v181, v197, v202
	ds_read_b64_tr_b16 v[192:193], v212
	ds_read_b64_tr_b16 v[196:197], v212 offset:32
	s_waitcnt lgkmcnt(1)
	v_mfma_f32_16x16x16_bf16 v[192:195], v[192:193], v[180:181], v[198:201]
	s_nop 2
	ds_read_b64_tr_b16 v[200:201], v212 offset:64
	v_add_f32_e32 v78, v78, v79
	v_div_scale_f32 v79, s[0:1], v78, v78, 1.0
	s_waitcnt lgkmcnt(1)
	v_mfma_f32_16x16x16_bf16 v[196:199], v[196:197], v[180:181], v[204:207]
	s_nop 2
	ds_read_b64_tr_b16 v[204:205], v212 offset:96
	s_waitcnt lgkmcnt(1)
	v_mfma_f32_16x16x16_bf16 v[200:203], v[200:201], v[180:181], v[208:211]
	s_waitcnt lgkmcnt(0)
	v_mfma_f32_16x16x16_bf16 v[204:207], v[204:205], v[180:181], v[218:221]
	v_cvt_pk_bf16_f32 v180, v186, v187
	v_mad_u64_u32 v[186:187], s[0:1], v161, s27, v[88:89]
	v_cvt_pk_bf16_f32 v181, v189, v190
	ds_read_b64_tr_b16 v[190:191], v186
	ds_read_b64_tr_b16 v[208:209], v186 offset:32
	s_waitcnt lgkmcnt(1)
	v_mfma_f32_16x16x16_bf16 v[190:193], v[190:191], v[180:181], v[192:195]
	s_waitcnt lgkmcnt(0)
	v_mfma_f32_16x16x16_bf16 v[194:197], v[208:209], v[180:181], v[196:199]
	v_mad_u64_u32 v[208:209], s[0:1], v160, s27, v[88:89]
	v_add_u32_e32 v160, 0xc0, v91
	s_nop 0
	ds_read_b64_tr_b16 v[198:199], v186 offset:64
	ds_read_b64_tr_b16 v[186:187], v186 offset:96
	s_waitcnt lgkmcnt(1)
	v_mfma_f32_16x16x16_bf16 v[198:201], v[198:199], v[180:181], v[200:203]
	v_add_u32_e32 v161, v160, v107
	v_add_u32_e32 v160, v160, v110
	s_waitcnt lgkmcnt(0)
	v_mfma_f32_16x16x16_bf16 v[202:205], v[186:187], v[180:181], v[204:207]
	s_nop 2
	v_cvt_pk_bf16_f32 v206, v183, v184
	v_cvt_pk_bf16_f32 v207, v185, v188
	ds_read_b64_tr_b16 v[180:181], v208
	ds_read_b64_tr_b16 v[184:185], v208 offset:32
	ds_read_b64_tr_b16 v[188:189], v208 offset:64
	s_waitcnt lgkmcnt(2)
	v_mfma_f32_16x16x16_bf16 v[180:183], v[180:181], v[206:207], v[190:193]
	s_nop 2
	ds_read_b64_tr_b16 v[192:193], v208 offset:96
	s_waitcnt lgkmcnt(1)
	v_mfma_f32_16x16x16_bf16 v[188:191], v[188:189], v[206:207], v[198:201]
	s_nop 2
	v_mad_u64_u32 v[198:199], s[0:1], v161, s27, v[88:89]
	v_mfma_f32_16x16x16_bf16 v[184:187], v[184:185], v[206:207], v[194:197]
	s_nop 2
	v_cvt_pk_bf16_f32 v196, v171, v175
	v_cvt_pk_bf16_f32 v197, v177, v178
	ds_read_b64_tr_b16 v[174:175], v198
	ds_read_b64_tr_b16 v[178:179], v198 offset:32
	s_waitcnt lgkmcnt(1)
	v_mfma_f32_16x16x16_bf16 v[174:177], v[174:175], v[196:197], v[180:183]
	s_nop 2
	ds_read_b64_tr_b16 v[182:183], v198 offset:64
	s_waitcnt lgkmcnt(1)
	v_mfma_f32_16x16x16_bf16 v[178:181], v[178:179], v[196:197], v[184:187]
	s_nop 2
	ds_read_b64_tr_b16 v[186:187], v198 offset:96
	v_mfma_f32_16x16x16_bf16 v[192:195], v[192:193], v[206:207], v[202:205]
	s_waitcnt lgkmcnt(1)
	v_mfma_f32_16x16x16_bf16 v[182:185], v[182:183], v[196:197], v[188:191]
	s_waitcnt lgkmcnt(0)
	v_mfma_f32_16x16x16_bf16 v[186:189], v[186:187], v[196:197], v[192:195]
	s_nop 0
	v_cvt_pk_bf16_f32 v190, v168, v169
	v_cvt_pk_bf16_f32 v191, v170, v172
	s_nop 0
	v_mad_u64_u32 v[192:193], s[0:1], v160, s27, v[88:89]
	ds_read_b64_tr_b16 v[168:169], v192
	ds_read_b64_tr_b16 v[172:173], v192 offset:32
	s_waitcnt lgkmcnt(1)
	v_mfma_f32_16x16x16_bf16 v[168:171], v[168:169], v[190:191], v[174:177]
	s_nop 2
	ds_read_b64_tr_b16 v[176:177], v192 offset:64
	v_add_u32_e32 v160, 0x100, v91
	v_add_u32_e32 v161, v160, v107
	s_waitcnt lgkmcnt(1)
; DI f32x4 mfma16(s16x4 a, s16x4 b, f32x4 c) { return __builtin_amdgcn_mfma_f32_16x16x16bf16_1k(a, b, c, 0, 0, 0); }
; DI s16x4 pack4(f32x4 v) { uint2 w; w.x = pk(v[0], v[1]); w.y = pk(v[2], v[3]); return __builtin_bit_cast(s16x4, w); }
; DI void phase_na(const Ctx& c, LAS unsigned char* lds, int g, int l, const bf16* PROJ, bf16* MIX, int bid, int nb, int tid) {
;     ...
;         for (int t = 0; t < 16; ++t) { const int rr = t >> 1, hf = t & 1, krow = (r0 + rr - rbase) * 64 + kb0 + 16 * hf; const s16x4 pb = pack4(sc[t]);
; #pragma unroll
;             for (int dt = 0; dt < 4; ++dt) o[dt] = mfma16(ld_tr4(Vimg, 72, krow, dt * 16, lane), pb, o[dt]); }
	v_mfma_f32_16x16x16_bf16 v[172:175], v[172:173], v[190:191], v[178:181]
	v_add_u32_e32 v155, v160, v110
	s_nop 1
	ds_read_b64_tr_b16 v[180:181], v192 offset:96
	s_waitcnt lgkmcnt(1)
	v_mfma_f32_16x16x16_bf16 v[176:179], v[176:177], v[190:191], v[182:185]
	s_nop 2
	v_cvt_pk_bf16_f32 v184, v164, v165
	s_waitcnt lgkmcnt(0)
	v_mfma_f32_16x16x16_bf16 v[180:183], v[180:181], v[190:191], v[186:189]
	s_nop 2
	v_mad_u64_u32 v[186:187], s[0:1], v161, s27, v[88:89]
	ds_read_b64_tr_b16 v[164:165], v186
	ds_read_b64_tr_b16 v[188:189], v186 offset:32
	v_cvt_pk_bf16_f32 v185, v166, v167
	s_waitcnt lgkmcnt(1)
	s_nop 0
	v_mfma_f32_16x16x16_bf16 v[164:167], v[164:165], v[184:185], v[168:171]
	s_waitcnt lgkmcnt(0)
	v_mfma_f32_16x16x16_bf16 v[168:171], v[188:189], v[184:185], v[172:175]
	s_nop 2
	ds_read_b64_tr_b16 v[172:173], v186 offset:64
	s_waitcnt lgkmcnt(0)
	v_mfma_f32_16x16x16_bf16 v[172:175], v[172:173], v[184:185], v[176:179]
	s_nop 2
	ds_read_b64_tr_b16 v[176:177], v186 offset:96
	s_waitcnt lgkmcnt(0)
	v_mfma_f32_16x16x16_bf16 v[176:179], v[176:177], v[184:185], v[180:183]
	s_nop 2
	v_mad_u64_u32 v[180:181], s[0:1], v155, s27, v[88:89]
	ds_read_b64_tr_b16 v[182:183], v180
	ds_read_b64_tr_b16 v[184:185], v180 offset:32
	s_waitcnt lgkmcnt(1)
	v_mfma_f32_16x16x16_bf16 v[164:167], v[182:183], v[156:157], v[164:167]
	ds_read_b64_tr_b16 v[182:183], v180 offset:64
	ds_read_b64_tr_b16 v[180:181], v180 offset:96
	s_waitcnt lgkmcnt(2)
	v_mfma_f32_16x16x16_bf16 v[168:171], v[184:185], v[156:157], v[168:171]
	s_waitcnt lgkmcnt(1)
	v_mfma_f32_16x16x16_bf16 v[172:175], v[182:183], v[156:157], v[172:175]
	s_waitcnt lgkmcnt(0)
	v_mfma_f32_16x16x16_bf16 v[176:179], v[180:181], v[156:157], v[176:179]
	v_cvt_pk_bf16_f32 v156, v151, v152
	v_add_u32_e32 v151, v159, v107
	v_mad_u64_u32 v[180:181], s[0:1], v151, s27, v[88:89]
	v_cvt_pk_bf16_f32 v157, v153, v154
	ds_read_b64_tr_b16 v[152:153], v180
	ds_read_b64_tr_b16 v[182:183], v180 offset:32
	s_waitcnt lgkmcnt(1)
	v_mfma_f32_16x16x16_bf16 v[152:155], v[152:153], v[156:157], v[164:167]
	s_waitcnt lgkmcnt(0)
	v_mfma_f32_16x16x16_bf16 v[164:167], v[182:183], v[156:157], v[168:171]
	s_nop 2
	ds_read_b64_tr_b16 v[168:169], v180 offset:64
	s_waitcnt lgkmcnt(0)
	v_mfma_f32_16x16x16_bf16 v[168:171], v[168:169], v[156:157], v[172:175]
	s_nop 2
	ds_read_b64_tr_b16 v[172:173], v180 offset:96
	s_waitcnt lgkmcnt(0)
	v_mfma_f32_16x16x16_bf16 v[172:175], v[172:173], v[156:157], v[176:179]
	v_cvt_pk_bf16_f32 v156, v147, v148
	v_add_u32_e32 v147, v159, v110
	s_nop 0
	v_mad_u64_u32 v[176:177], s[0:1], v147, s27, v[88:89]
	v_cvt_pk_bf16_f32 v157, v149, v150
	ds_read_b64_tr_b16 v[148:149], v176
	ds_read_b64_tr_b16 v[178:179], v176 offset:32
	s_waitcnt lgkmcnt(1)
	v_mfma_f32_16x16x16_bf16 v[148:151], v[148:149], v[156:157], v[152:155]
	v_add_u32_e32 v159, 0x180, v91
	v_add_u32_e32 v91, 0x1c0, v91
	v_add_u32_e32 v93, v91, v107
	s_waitcnt lgkmcnt(0)
	v_mfma_f32_16x16x16_bf16 v[152:155], v[178:179], v[156:157], v[164:167]
	s_nop 2
	ds_read_b64_tr_b16 v[164:165], v176 offset:64
	s_waitcnt lgkmcnt(0)
	v_mfma_f32_16x16x16_bf16 v[164:167], v[164:165], v[156:157], v[168:171]
	s_nop 2
	ds_read_b64_tr_b16 v[168:169], v176 offset:96
	s_waitcnt lgkmcnt(0)
	v_mfma_f32_16x16x16_bf16 v[168:171], v[168:169], v[156:157], v[172:175]
	v_cvt_pk_bf16_f32 v156, v143, v144
	v_add_u32_e32 v143, v159, v107
	s_nop 0
	v_mad_u64_u32 v[172:173], s[0:1], v143, s27, v[88:89]
	v_cvt_pk_bf16_f32 v157, v145, v146
	ds_read_b64_tr_b16 v[144:145], v172
	ds_read_b64_tr_b16 v[174:175], v172 offset:32
	s_waitcnt lgkmcnt(1)
	v_mfma_f32_16x16x16_bf16 v[144:147], v[144:145], v[156:157], v[148:151]
	s_waitcnt lgkmcnt(0)
	v_mfma_f32_16x16x16_bf16 v[148:151], v[174:175], v[156:157], v[152:155]
	s_nop 2
	ds_read_b64_tr_b16 v[152:153], v172 offset:64
	s_waitcnt lgkmcnt(0)
	v_mfma_f32_16x16x16_bf16 v[152:155], v[152:153], v[156:157], v[164:167]
	s_nop 2
	ds_read_b64_tr_b16 v[164:165], v172 offset:96
	s_waitcnt lgkmcnt(0)
; DI unsigned pk(float lo, float hi) { return pg8::cvt_pk_bf16(lo, hi); }
; DI f32x4 mfma16(s16x4 a, s16x4 b, f32x4 c) { return __builtin_amdgcn_mfma_f32_16x16x16bf16_1k(a, b, c, 0, 0, 0); }
; DI s16x4 pack4(f32x4 v) { uint2 w; w.x = pk(v[0], v[1]); w.y = pk(v[2], v[3]); return __builtin_bit_cast(s16x4, w); }
; DI void phase_na(const Ctx& c, LAS unsigned char* lds, int g, int l, const bf16* PROJ, bf16* MIX, int bid, int nb, int tid) {
;     ...
;         for (int t = 0; t < 16; ++t) { const int rr = t >> 1, hf = t & 1, krow = (r0 + rr - rbase) * 64 + kb0 + 16 * hf; const s16x4 pb = pack4(sc[t]);
; #pragma unroll
;             for (int dt = 0; dt < 4; ++dt) o[dt] = mfma16(ld_tr4(Vimg, 72, krow, dt * 16, lane), pb, o[dt]); }
;         const float inv = 1.0f / sum;
; #pragma unroll
;         for (int dt = 0; dt < 4; ++dt) { uint2 wv; wv.x = pk(o[dt][0] * inv, o[dt][1] * inv); wv.y = pk(o[dt][2] * inv, o[dt][3] * inv);
;             *(uint2*)(MIX + (size_t)qtok * DM + h * 64 + dt * 16 + gq * 4) = wv; }
;         __syncthreads();
	v_mfma_f32_16x16x16_bf16 v[164:167], v[164:165], v[156:157], v[168:171]
	v_cvt_pk_bf16_f32 v156, v139, v140
	v_add_u32_e32 v139, v159, v110
	s_nop 0
	v_mad_u64_u32 v[168:169], s[0:1], v139, s27, v[88:89]
	v_cvt_pk_bf16_f32 v157, v141, v142
	ds_read_b64_tr_b16 v[140:141], v168
	ds_read_b64_tr_b16 v[170:171], v168 offset:32
	s_waitcnt lgkmcnt(1)
	v_mfma_f32_16x16x16_bf16 v[140:143], v[140:141], v[156:157], v[144:147]
	s_waitcnt lgkmcnt(0)
	v_mfma_f32_16x16x16_bf16 v[144:147], v[170:171], v[156:157], v[148:151]
	s_nop 2
	ds_read_b64_tr_b16 v[148:149], v168 offset:64
	s_waitcnt lgkmcnt(0)
	v_mfma_f32_16x16x16_bf16 v[148:151], v[148:149], v[156:157], v[152:155]
	s_nop 2
	ds_read_b64_tr_b16 v[152:153], v168 offset:96
	s_waitcnt lgkmcnt(0)
	v_mfma_f32_16x16x16_bf16 v[152:155], v[152:153], v[156:157], v[164:167]
	v_mad_u64_u32 v[156:157], s[0:1], v93, s27, v[88:89]
	ds_read_b64_tr_b16 v[138:139], v156
	s_nop 0
	ds_read_b64_tr_b16 v[164:165], v156 offset:32
	s_waitcnt lgkmcnt(1)
	v_mfma_f32_16x16x16_bf16 v[138:141], v[138:139], v[84:85], v[140:143]
	s_waitcnt lgkmcnt(0)
	v_mfma_f32_16x16x16_bf16 v[142:145], v[164:165], v[84:85], v[144:147]
	s_nop 2
	ds_read_b64_tr_b16 v[146:147], v156 offset:64
	s_waitcnt lgkmcnt(0)
	v_mfma_f32_16x16x16_bf16 v[146:149], v[146:147], v[84:85], v[148:151]
	s_nop 2
	ds_read_b64_tr_b16 v[150:151], v156 offset:96
	s_waitcnt lgkmcnt(0)
	v_mfma_f32_16x16x16_bf16 v[150:153], v[150:151], v[84:85], v[152:155]
	v_cvt_pk_bf16_f32 v84, v80, v81
	v_add_u32_e32 v80, v91, v110
	s_nop 0
	v_mad_u64_u32 v[154:155], s[0:1], v80, s27, v[88:89]
	ds_read_b64_tr_b16 v[80:81], v154
	ds_read_b64_tr_b16 v[156:157], v154 offset:32
	v_cvt_pk_bf16_f32 v85, v82, v83
	v_readlane_b32 s0, v252, 22
	v_readlane_b32 s1, v252, 23
	s_waitcnt lgkmcnt(1)
	v_mfma_f32_16x16x16_bf16 v[80:83], v[80:81], v[84:85], v[138:141]
	s_waitcnt lgkmcnt(0)
	v_mfma_f32_16x16x16_bf16 v[138:141], v[156:157], v[84:85], v[142:145]
	s_nop 2
	ds_read_b64_tr_b16 v[142:143], v154 offset:64
	s_waitcnt lgkmcnt(0)
	v_mfma_f32_16x16x16_bf16 v[142:145], v[142:143], v[84:85], v[146:149]
	s_nop 2
	ds_read_b64_tr_b16 v[146:147], v154 offset:96
	s_waitcnt lgkmcnt(0)
	v_mfma_f32_16x16x16_bf16 v[146:149], v[146:147], v[84:85], v[150:153]
	v_rcp_f32_e32 v84, v79
	s_nop 0
	v_fma_f32 v85, -v79, v84, 1.0
	v_fmac_f32_e32 v84, v85, v84
	v_div_scale_f32 v85, vcc, 1.0, v78, 1.0
	v_mul_f32_e32 v91, v85, v84
	v_fma_f32 v93, -v79, v91, v85
	v_fmac_f32_e32 v91, v93, v84
	v_fma_f32 v79, -v79, v91, v85
	v_div_fmas_f32 v79, v79, v84, v91
	v_lshlrev_b64 v[84:85], 11, v[94:95]
	v_div_fixup_f32 v78, v79, v78, 1.0
	v_lshl_add_u64 v[84:85], s[0:1], 0, v[84:85]
	v_lshl_add_u64 v[84:85], s[6:7], 1, v[84:85]
	v_mov_b32_e32 v93, v0
	v_pk_mul_f32 v[80:81], v[78:79], v[80:81] op_sel_hi:[0,1]
	v_pk_mul_f32 v[82:83], v[78:79], v[82:83] op_sel_hi:[0,1]
	v_lshl_add_u64 v[84:85], v[84:85], 0, v[92:93]
	v_cvt_pk_bf16_f32 v80, v80, v81
	v_cvt_pk_bf16_f32 v81, v82, v83
	global_store_dwordx2 v[84:85], v[80:81], off
	v_pk_mul_f32 v[80:81], v[78:79], v[138:139] op_sel_hi:[0,1]
	v_pk_mul_f32 v[82:83], v[78:79], v[140:141] op_sel_hi:[0,1]
	v_cvt_pk_bf16_f32 v80, v80, v81
	v_cvt_pk_bf16_f32 v81, v82, v83
	global_store_dwordx2 v[84:85], v[80:81], off offset:32
	v_pk_mul_f32 v[80:81], v[78:79], v[142:143] op_sel_hi:[0,1]
	v_pk_mul_f32 v[82:83], v[78:79], v[144:145] op_sel_hi:[0,1]
	v_cvt_pk_bf16_f32 v80, v80, v81
	v_cvt_pk_bf16_f32 v81, v82, v83
	global_store_dwordx2 v[84:85], v[80:81], off offset:64
	v_pk_mul_f32 v[80:81], v[78:79], v[146:147] op_sel_hi:[0,1]
	v_pk_mul_f32 v[78:79], v[78:79], v[148:149] op_sel_hi:[0,1]
	v_cvt_pk_bf16_f32 v80, v80, v81
	v_cvt_pk_bf16_f32 v81, v78, v79
	s_andn2_b64 vcc, exec, s[8:9]
	s_mov_b32 s0, s10
	global_store_dwordx2 v[84:85], v[80:81], off offset:96
	s_barrier
	s_cbranch_vccz .LBB0_218

; DI void phase_na(const Ctx& c, LAS unsigned char* lds, int g, int l, const bf16* PROJ, bf16* MIX, int bid, int nb, int tid) {
;     ...
;         __syncthreads();
;         if (iu + wpx < upx) NA_PREFETCH(xcd * upx + iu + wpx);
.LBB0_216:
	s_or_b64 exec, exec, s[8:9]
	s_add_i32 s10, s0, s14
	s_cmp_ge_i32 s10, s12
	s_cselect_b64 s[8:9], -1, 0
	s_and_b64 vcc, exec, s[8:9]
	s_waitcnt vmcnt(0) lgkmcnt(0)
	s_barrier
	s_cbranch_vccnz .LBB0_211
	s_add_i32 s0, s20, s0
	s_and_b32 s11, s0, 0x7f
	s_and_b32 s19, s11, s92
	s_lshl_b32 s33, s19, 1
	s_add_i32 s33, s33, -4
	s_lshr_b32 s11, s11, s58
	s_min_i32 s33, s33, s62
	s_cmp_gt_u32 s19, 1
	s_cselect_b32 s19, s33, 0
	s_lshl_b32 s11, s11, s59
	v_add_u32_e32 v6, s19, v89
	v_add_u32_e32 v14, s19, v96
	v_add_u32_e32 v22, s19, v97
	v_add_u32_e32 v30, s19, v98
	v_add_u32_e32 v38, s19, v99
	v_add_u32_e32 v46, s19, v100
	v_add_u32_e32 v54, s19, v101
	v_add_u32_e32 v62, s19, v102
	v_add_u32_e32 v73, s19, v103
	v_or_b32_e32 v72, s11, v5
	s_ashr_i32 s0, s0, 1
	v_min_i32_e32 v6, s63, v6
	v_min_i32_e32 v14, s63, v14
	v_min_i32_e32 v22, s63, v22
	v_min_i32_e32 v30, s63, v30
	v_min_i32_e32 v38, s63, v38
	v_min_i32_e32 v46, s63, v46
	v_min_i32_e32 v54, s63, v54
	v_min_i32_e32 v62, s63, v62
	v_min_i32_e32 v73, s63, v73
	s_and_b32 s34, s0, 0xffffffc0
	v_lshl_add_u32 v6, v6, 6, v72
	v_lshl_add_u32 v14, v14, 6, v72
	v_lshl_add_u32 v22, v22, 6, v72
	v_lshl_add_u32 v30, v30, 6, v72
	v_lshl_add_u32 v38, v38, 6, v72
	v_lshl_add_u32 v46, v46, 6, v72
	v_lshl_add_u32 v54, v54, 6, v72
	v_lshl_add_u32 v62, v62, 6, v72
	v_lshl_add_u32 v72, v73, 6, v72
	s_ashr_i32 s35, s34, 31
	v_ashrrev_i32_e32 v7, 31, v6
	v_ashrrev_i32_e32 v15, 31, v14
	v_ashrrev_i32_e32 v23, 31, v22
	v_ashrrev_i32_e32 v31, 31, v30
	v_ashrrev_i32_e32 v39, 31, v38
	v_ashrrev_i32_e32 v47, 31, v46
	v_ashrrev_i32_e32 v55, 31, v54
	v_ashrrev_i32_e32 v63, 31, v62
	v_ashrrev_i32_e32 v73, 31, v72
	v_lshl_add_u64 v[70:71], s[34:35], 1, v[86:87]
	v_lshlrev_b64 v[6:7], 13, v[6:7]
	v_lshlrev_b64 v[14:15], 13, v[14:15]
	v_lshlrev_b64 v[22:23], 13, v[22:23]
	v_lshlrev_b64 v[30:31], 13, v[30:31]
	v_lshlrev_b64 v[38:39], 13, v[38:39]
	v_lshlrev_b64 v[46:47], 13, v[46:47]
	v_lshlrev_b64 v[54:55], 13, v[54:55]
	v_lshlrev_b64 v[62:63], 13, v[62:63]
	v_lshlrev_b64 v[72:73], 13, v[72:73]
	v_lshl_add_u64 v[10:11], v[70:71], 0, v[6:7]
	v_lshl_add_u64 v[18:19], v[70:71], 0, v[14:15]
	v_lshl_add_u64 v[26:27], v[70:71], 0, v[22:23]
	v_lshl_add_u64 v[34:35], v[70:71], 0, v[30:31]
	v_lshl_add_u64 v[42:43], v[70:71], 0, v[38:39]
	v_lshl_add_u64 v[50:51], v[70:71], 0, v[46:47]
	v_lshl_add_u64 v[58:59], v[70:71], 0, v[54:55]
	v_lshl_add_u64 v[66:67], v[70:71], 0, v[62:63]
	v_lshl_add_u64 v[74:75], v[70:71], 0, v[72:73]
	global_load_dwordx4 v[6:9], v[10:11], off offset:1024
	s_nop 0
	global_load_dwordx4 v[10:13], v[10:11], off offset:512
	s_nop 0
	global_load_dwordx4 v[14:17], v[18:19], off offset:1024
	s_nop 0
	global_load_dwordx4 v[18:21], v[18:19], off offset:512
	s_nop 0
	global_load_dwordx4 v[22:25], v[26:27], off offset:1024
	s_nop 0
	global_load_dwordx4 v[26:29], v[26:27], off offset:512
	s_nop 0
	global_load_dwordx4 v[30:33], v[34:35], off offset:1024
	s_nop 0
	global_load_dwordx4 v[34:37], v[34:35], off offset:512
	s_nop 0
	global_load_dwordx4 v[38:41], v[42:43], off offset:1024
	s_nop 0
	global_load_dwordx4 v[42:45], v[42:43], off offset:512
	s_nop 0
	global_load_dwordx4 v[46:49], v[50:51], off offset:1024
	s_nop 0
	global_load_dwordx4 v[50:53], v[50:51], off offset:512
	s_nop 0
	global_load_dwordx4 v[54:57], v[58:59], off offset:1024
	s_nop 0
	global_load_dwordx4 v[58:61], v[58:59], off offset:512
	s_nop 0
	global_load_dwordx4 v[62:65], v[66:67], off offset:1024
	s_nop 0
	global_load_dwordx4 v[66:69], v[66:67], off offset:512
	s_nop 0
	global_load_dwordx4 v[70:73], v[74:75], off offset:1024
	s_nop 0
	global_load_dwordx4 v[74:77], v[74:75], off offset:512
	s_branch .LBB0_211
